# on top of previous: in the grid barrier leader path the local-release atomic (XGEN add) is issued before the leader's own buffer_inv sc1 instead of after it
# speedup vs baseline: 1.0034x; 1.0034x over previous
; __device__ __forceinline__ unsigned xb_ld(unsigned* p)              { return __hip_atomic_load(p, __ATOMIC_RELAXED, __HIP_MEMORY_SCOPE_AGENT); }
; __device__ __forceinline__ unsigned xb_add(unsigned* p, unsigned v) { return __hip_atomic_fetch_add(p, v, __ATOMIC_RELAXED, __HIP_MEMORY_SCOPE_AGENT); }
; #define XB_SPIN(cond, bar) do { unsigned _sp = 0; while (cond) { __builtin_amdgcn_s_sleep(1); \
;     if ((++_sp & 255u) == 0u) { if (xb_ld(&(bar)[XB_TMO])) break; if (_sp > XB_SPIN_CAP) { atomicAdd(&(bar)[XB_TMO], 1u); break; } } } } while (0)
; __device__ __forceinline__ void xcd_barrier(const XcdBarrier& b) {
;     ...
;         if (old + 1u == (gen + 1u) * nloc) {
;             __builtin_amdgcn_fence(__ATOMIC_RELEASE, "agent");
;             asm volatile("s_waitcnt vmcnt(0)" ::: "memory");
;             const unsigned og = xb_add(&bar[XB_TOP], 1u);
;             const unsigned tg = og / nx;
;             if (og + 1u == (tg + 1u) * nx) xb_add(&bar[XB_TOPGEN], 1u);
;             else XB_SPIN(xb_ld(&bar[XB_TOPGEN]) == tg, bar);
;             __builtin_amdgcn_fence(__ATOMIC_ACQUIRE, "agent");
;             xb_add(&bar[XB_XGEN(b.x)], 1u);
;             asm volatile("s_waitcnt vmcnt(0)" ::: "memory");
.LBB0_36:
	s_or_b64 exec, exec, s[2:3]
	v_mov_b32_e32 v1, s23
	v_add_co_u32_e32 v2, vcc, 0x2000, v1
	v_mov_b32_e32 v1, s22
	s_nop 0
	v_addc_co_u32_e32 v3, vcc, 0, v1, vcc
	s_waitcnt vmcnt(0) lgkmcnt(0)
	flat_atomic_add v[2:3], v243 offset:1024
	buffer_inv sc1
	s_waitcnt vmcnt(0)
